# seam/flag poll loops spin with s_nop 7 instead of s_sleep (22 sites), on top of pollfast
# baseline (speedup 1.0000x reference)
.LBB0_165:
	global_load_dword v3, v2, s[18:19] sc1
	s_waitcnt vmcnt(0)
	v_readfirstlane_b32 s2, v3
	s_cmp_ge_u32 s2, s75
	s_mov_b64 s[2:3], -1
	s_cbranch_scc1 .LBB0_164
	s_mov_b64 s[2:3], 0
	s_nop 7
	s_branch .LBB0_164

.LBB0_216:
	s_nop 7
	global_load_dword v2, v0, s[6:7] offset:32 sc1
	s_waitcnt vmcnt(0)
	v_and_b32_e32 v2, 0xffff0000, v2
	v_cmp_ne_u32_e32 vcc, v2, v1
	s_or_b64 s[10:11], vcc, s[10:11]
	s_andn2_b64 exec, exec, s[10:11]
	s_cbranch_execnz .LBB0_216

.LBB0_280:
	global_load_dword v1, v0, s[4:5] sc1
	s_waitcnt vmcnt(0)
	v_readfirstlane_b32 s6, v1
	s_cmp_ge_u32 s6, s75
	s_mov_b64 s[6:7], -1
	s_cbranch_scc1 .LBB0_279
	s_mov_b64 s[6:7], 0
	s_nop 7
	s_branch .LBB0_279

.LBB0_303:
	global_load_dword v0, v149, s[38:39] offset:1792 sc1
	s_waitcnt vmcnt(0)
	v_readfirstlane_b32 s10, v0
	s_cmp_gt_u32 s10, 7
	s_mov_b64 s[10:11], -1
	s_cbranch_scc1 .LBB0_302
	s_mov_b64 s[10:11], 0
	s_nop 7
	s_branch .LBB0_302

.LBB0_359:
	global_load_dword v0, v149, s[38:39] offset:1536 sc1
	s_waitcnt vmcnt(0)
	v_readfirstlane_b32 s10, v0
	s_cmp_gt_u32 s10, 63
	s_mov_b64 s[10:11], -1
	s_cbranch_scc1 .LBB0_358
	s_mov_b64 s[10:11], 0
	s_nop 7
	s_branch .LBB0_358

.LBB0_419:
	global_load_dword v1, v0, s[4:5] sc1
	s_waitcnt vmcnt(0)
	v_readfirstlane_b32 s6, v1
	s_cmp_ge_u32 s6, s8
	s_mov_b64 s[6:7], -1
	s_cbranch_scc1 .LBB0_418
	s_mov_b64 s[6:7], 0
	s_nop 7
	s_branch .LBB0_418

.LBB0_560:
	global_load_dword v1, v0, s[38:39] offset:256 sc1
	s_waitcnt vmcnt(0)
	v_readfirstlane_b32 s2, v1
	s_cmp_ge_u32 s2, s75
	s_mov_b64 s[2:3], -1
	s_cbranch_scc1 .LBB0_559
	s_mov_b64 s[2:3], 0
	s_nop 7
	s_branch .LBB0_559

.LBB0_587:
	global_load_dword v129, v128, s[20:21] sc1
	s_waitcnt vmcnt(0)
	v_readfirstlane_b32 s22, v129
	s_cmp_gt_u32 s22, 2
	s_mov_b64 s[22:23], -1
	s_cbranch_scc1 .LBB0_586
	s_mov_b64 s[22:23], 0
	s_nop 7
	s_branch .LBB0_586

.LBB0_638:
	global_load_dword v1, v0, s[4:5] sc1
	s_waitcnt vmcnt(0)
	v_readfirstlane_b32 s6, v1
	s_cmp_ge_u32 s6, s10
	s_mov_b64 s[6:7], -1
	s_cbranch_scc1 .LBB0_637
	s_mov_b64 s[6:7], 0
	s_nop 7
	s_branch .LBB0_637

.LBB0_915:
	global_load_dword v1, v0, s[4:5] sc1
	s_waitcnt vmcnt(0)
	v_readfirstlane_b32 s6, v1
	s_cmp_ge_u32 s6, s85
	s_mov_b64 s[6:7], -1
	s_cbranch_scc1 .LBB0_914
	s_mov_b64 s[6:7], 0
	s_nop 7
	s_branch .LBB0_914

.LBB0_944:
	global_load_dword v0, v1, s[38:39] offset:1024 sc1
	s_waitcnt vmcnt(0)
	v_readfirstlane_b32 s4, v0
	s_cmp_gt_u32 s4, 7
	s_mov_b64 s[4:5], -1
	s_cbranch_scc1 .LBB0_943
	s_mov_b64 s[4:5], 0
	s_nop 7
	s_branch .LBB0_943

.LBB0_999:
	global_load_dword v0, v1, s[38:39] offset:768 sc1
	s_waitcnt vmcnt(0)
	v_readfirstlane_b32 s4, v0
	s_cmpk_gt_u32 s4, 0xff
	s_mov_b64 s[4:5], -1
	s_cbranch_scc1 .LBB0_998
	s_mov_b64 s[4:5], 0
	s_nop 7
	s_branch .LBB0_998

.LBB0_1281:
	global_load_dword v1, v0, s[38:39] offset:512 sc1
	s_waitcnt vmcnt(0)
	v_readfirstlane_b32 s0, v1
	s_cmp_ge_u32 s0, s75
	s_mov_b64 s[0:1], -1
	s_cbranch_scc1 .LBB0_1280
	s_mov_b64 s[0:1], 0
	s_nop 7
	s_branch .LBB0_1280

.LBB0_1343:
	global_load_dword v1, v0, s[2:3] sc1
	s_waitcnt vmcnt(0)
	v_readfirstlane_b32 s4, v1
	s_cmp_ge_u32 s4, s6
	s_mov_b64 s[4:5], -1
	s_cbranch_scc1 .LBB0_1342
	s_mov_b64 s[4:5], 0
	s_nop 7
	s_branch .LBB0_1342
